# prompt-scan state clear also with 64-bit moves (on top of the GEMM accumulator clears)
# speedup vs baseline: 1.0071x; 1.0071x over previous
.LBB0_778:
	s_ashr_i32 s6, s22, 7
	s_ashr_i32 s0, s22, 8
	s_or_b32 s24, s9, 0x80
	s_or_b32 s25, s23, 0x800
	s_xor_b32 s7, s6, s0
	s_and_b64 s[0:1], s[40:41], exec
	s_movk_i32 s1, 0x4400
	s_movk_i32 s0, 0x300
	s_cselect_b32 s1, s1, 0x15400
	s_cselect_b32 s0, 0x100, s0
	s_add_i32 s26, s1, 0
	s_lshl_b32 s1, s28, 5
	s_and_b32 s22, s1, 32
	s_lshl_b32 s27, s7, 5
	s_or_b32 s28, s23, s22
	s_lshl_b32 s23, s6, 5
	s_cmp_gt_i32 s7, -1
	s_cselect_b64 s[50:51], -1, 0
	s_lshl_b32 s1, s6, 6
	s_add_i32 s29, s1, 0
	s_add_i32 s30, s0, 0
	v_mov_b32_e32 v0, 0
	s_add_i32 s29, s29, 0x1dc00
	s_add_i32 s30, s30, 0x23000
	s_or_b32 s31, s31, s34
	s_add_i32 s34, s7, 1
	s_mov_b32 s35, 0
	s_mov_b64 s[52:53], 0
	v_mov_b32_e32 v1, v0
	v_mov_b64_e32 v[2:3], v[0:1]
	v_mov_b64_e32 v[4:5], v[0:1]
	v_mov_b64_e32 v[6:7], v[0:1]
	v_mov_b64_e32 v[8:9], v[0:1]
	v_mov_b64_e32 v[10:11], v[0:1]
	v_mov_b64_e32 v[12:13], v[0:1]
	v_mov_b64_e32 v[14:15], v[0:1]
	s_waitcnt lgkmcnt(0)
	s_barrier
	s_branch .LBB0_781
